# lever 1 on the mix-out GEMM epilogue: f32-residual load block waits once before joining the shared row-group code, the later counted waits (store/atomic drains) there removed
# speedup vs baseline: 1.0111x; 1.0001x over previous
;     __device__ __forceinline__ void operator()(const f32x4 (&acc)[2][2][4][2], const Unit& u, int wr, int wc, int fr, int fq) const {
;     ...
;         for (int aih = 0; aih < 4; ++aih) { const int ai = aih >> 1, m0 = (aih & 1) * 2;
;             f32x4 rv[4][2][2];
;             if (rb16) {
;                 u32x4 rw[2][2];
; #pragma unroll
;                 for (int m = m0; m < m0 + 2; ++m)
; #pragma unroll
;                     for (int bj = 0; bj < 2; ++bj) rw[m - m0][bj] = *(const u32x4*)((const bf16_t*)r0 + (size_t)(row0 + ai * HALF + m * 16) * D + col0 + bj * HALF);
; #pragma unroll
;                 for (int m = m0; m < m0 + 2; ++m)
; #pragma unroll
;                     for (int bj = 0; bj < 2; ++bj) { const u32x4 x = rw[m - m0][bj];
;                         rv[m][bj][0] = (f32x4){__builtin_bit_cast(float, x.x << 16), __builtin_bit_cast(float, x.x & 0xffff0000u), __builtin_bit_cast(float, x.y << 16), __builtin_bit_cast(float, x.y & 0xffff0000u)};
;                         rv[m][bj][1] = (f32x4){__builtin_bit_cast(float, x.z << 16), __builtin_bit_cast(float, x.z & 0xffff0000u), __builtin_bit_cast(float, x.w << 16), __builtin_bit_cast(float, x.w & 0xffff0000u)}; }
;             } else {
; #pragma unroll
;                 for (int m = m0; m < m0 + 2; ++m) { const float* rp = (const float*)r0 + (size_t)(row0 + ai * HALF + m * 16) * D + col0;
; #pragma unroll
;                     for (int bj = 0; bj < 2; ++bj) { rv[m][bj][0] = *(const f32x4*)(rp + bj * HALF); rv[m][bj][1] = *(const f32x4*)(rp + bj * HALF + 4); } }
;             }
; #pragma unroll
;             for (int m = m0; m < m0 + 2; ++m) { const int row = row0 + ai * HALF + m * 16;
;                 float ss = 0.f;
; #pragma unroll
;                 for (int bj = 0; bj < 2; ++bj) { const f32x4 v0 = acc[ai][bj][m][0] + rv[m][bj][0], v1 = acc[ai][bj][m][1] + rv[m][bj][1];
;                     if (out) { float* op = out + (size_t)row * D + col0 + bj * HALF; *(f32x4*)op = v0; *(f32x4*)(op + 4) = v1; }
;                     if (Hn) { ss += (v0[0] * v0[0] + v0[1] * v0[1]) + (v0[2] * v0[2] + v0[3] * v0[3]) + (v1[0] * v1[0] + v1[1] * v1[1]) + (v1[2] * v1[2] + v1[3] * v1[3]);
;                         u32x4 w; w.x = cvt_pk_bf16(v0[0], v0[1]); w.y = cvt_pk_bf16(v0[2], v0[3]); w.z = cvt_pk_bf16(v1[0], v1[1]); w.w = cvt_pk_bf16(v1[2], v1[3]);
.LBB0_1494:
	s_waitcnt lgkmcnt(0)
	v_lshlrev_b64 v[100:101], 13, v[138:139]
	v_lshl_add_u64 v[100:101], v[198:199], 0, v[100:101]
	v_ashrrev_i32_e32 v133, 31, v132
	global_load_dwordx4 v[128:131], v[100:101], off offset:16
	global_load_dwordx4 v[120:123], v[100:101], off
	global_load_dwordx4 v[124:127], v[100:101], off offset:528
	global_load_dwordx4 v[116:119], v[100:101], off offset:512
	v_lshlrev_b64 v[100:101], 13, v[132:133]
	v_lshl_add_u64 v[100:101], v[198:199], 0, v[100:101]
	global_load_dwordx4 v[112:115], v[100:101], off offset:16
	global_load_dwordx4 v[108:111], v[100:101], off
	global_load_dwordx4 v[104:107], v[100:101], off offset:528
	s_nop 0
	global_load_dwordx4 v[100:103], v[100:101], off offset:512
	v_mov_b64_e32 v[134:135], v[136:137]
	s_waitcnt vmcnt(0)
.LBB0_1495:
	s_and_b64 vcc, exec, s[44:45]
	s_cbranch_vccnz .Lepi_skip_1501
	v_pk_add_f32 v[94:95], v[94:95], v[122:123]
	v_pk_add_f32 v[92:93], v[92:93], v[120:121]
	v_mul_f32_e32 v121, v95, v95
	v_mul_f32_e32 v120, v93, v93
	v_pk_add_f32 v[96:97], v[96:97], v[128:129]
	v_fmac_f32_e32 v120, v92, v92
	v_fmac_f32_e32 v121, v94, v94
	v_add_f32_e32 v120, v120, v121
	v_mul_f32_e32 v121, v97, v97
	v_pk_add_f32 v[98:99], v[98:99], v[130:131]
	v_fmac_f32_e32 v121, v96, v96
	v_add_f32_e32 v120, v121, v120
	v_mul_f32_e32 v121, v99, v99
	v_pk_add_f32 v[90:91], v[90:91], v[118:119]
	v_pk_add_f32 v[88:89], v[88:89], v[116:117]
	v_fmac_f32_e32 v121, v98, v98
	v_cvt_pk_bf16_f32 v92, v92, v93
	v_cvt_pk_bf16_f32 v93, v94, v95
	v_cvt_pk_bf16_f32 v94, v96, v97
	v_cvt_pk_bf16_f32 v95, v98, v99
	v_pk_add_f32 v[96:97], v[86:87], v[126:127]
	v_pk_add_f32 v[98:99], v[84:85], v[124:125]
	v_mul_f32_e32 v85, v89, v89
	v_mul_f32_e32 v86, v91, v91
	v_fmac_f32_e32 v85, v88, v88
	v_fmac_f32_e32 v86, v90, v90
	v_add_f32_e32 v85, v85, v86
	v_mul_f32_e32 v86, v99, v99
	v_mul_f32_e32 v84, v97, v97
	v_fmac_f32_e32 v86, v98, v98
	v_fmac_f32_e32 v84, v96, v96
	v_add_f32_e32 v85, v86, v85
	v_add_f32_e32 v120, v121, v120
	v_add_f32_e32 v84, v84, v85
	v_and_b32_e32 v86, 64, v218
	v_add_f32_e32 v85, v84, v120
	v_xor_b32_e32 v84, 16, v218
	v_add_u32_e32 v118, 64, v86
	v_cmp_lt_i32_e32 vcc, v84, v118
	v_lshl_add_u64 v[86:87], s[8:9], 0, v[134:135]
	v_lshl_add_u64 v[116:117], v[190:191], 1, v[86:87]
	v_cndmask_b32_e32 v84, v218, v84, vcc
	v_lshlrev_b32_e32 v84, 2, v84
	ds_bpermute_b32 v119, v84, v85
	v_cvt_pk_bf16_f32 v88, v88, v89
	v_cvt_pk_bf16_f32 v89, v90, v91
	v_cvt_pk_bf16_f32 v90, v98, v99
	v_cvt_pk_bf16_f32 v91, v96, v97
	s_waitcnt lgkmcnt(0)
	v_add_f32_e32 v86, v85, v119
	v_xor_b32_e32 v85, 32, v218
	v_cmp_lt_i32_e32 vcc, v85, v118
	global_store_dwordx4 v[116:117], v[92:95], off
	global_store_dwordx4 v[116:117], v[88:91], off offset:256
	v_cndmask_b32_e32 v85, v218, v85, vcc
	v_lshlrev_b32_e32 v85, 2, v85
	ds_bpermute_b32 v87, v85, v86
	s_and_saveexec_b64 s[2:3], s[0:1]
	s_cbranch_execz .LBB0_1498
	v_lshl_add_u64 v[88:89], v[194:195], 2, s[6:7]
	s_waitcnt lgkmcnt(0)
	v_add_f32_e32 v86, v86, v87
	global_atomic_add_f32 v[88:89], v86, off offset:128
.LBB0_1498:
	s_or_b64 exec, exec, s[2:3]
	v_pk_add_f32 v[78:79], v[78:79], v[110:111]
	v_pk_add_f32 v[76:77], v[76:77], v[108:109]
	v_mul_f32_e32 v89, v79, v79
	v_mul_f32_e32 v88, v77, v77
	v_pk_add_f32 v[80:81], v[80:81], v[112:113]
	v_fmac_f32_e32 v88, v76, v76
	v_fmac_f32_e32 v89, v78, v78
	v_add_f32_e32 v88, v88, v89
	v_mul_f32_e32 v89, v81, v81
	v_pk_add_f32 v[82:83], v[82:83], v[114:115]
	v_fmac_f32_e32 v89, v80, v80
	v_add_f32_e32 v88, v89, v88
	v_mul_f32_e32 v89, v83, v83
	v_pk_add_f32 v[74:75], v[74:75], v[102:103]
	v_pk_add_f32 v[72:73], v[72:73], v[100:101]
	v_fmac_f32_e32 v89, v82, v82
	v_cvt_pk_bf16_f32 v76, v76, v77
	v_cvt_pk_bf16_f32 v77, v78, v79
	v_cvt_pk_bf16_f32 v78, v80, v81
	v_cvt_pk_bf16_f32 v79, v82, v83
	v_pk_add_f32 v[80:81], v[70:71], v[106:107]
	v_pk_add_f32 v[82:83], v[68:69], v[104:105]
	v_mul_f32_e32 v69, v73, v73
	v_mul_f32_e32 v70, v75, v75
	v_fmac_f32_e32 v69, v72, v72
	v_fmac_f32_e32 v70, v74, v74
	v_add_f32_e32 v69, v69, v70
	v_mul_f32_e32 v70, v83, v83
	v_mul_f32_e32 v68, v81, v81
	v_fmac_f32_e32 v70, v82, v82
	v_fmac_f32_e32 v68, v80, v80
	v_add_f32_e32 v69, v70, v69
	v_add_f32_e32 v88, v89, v88
	v_add_f32_e32 v68, v68, v69
	v_add_f32_e32 v71, v68, v88
	ds_bpermute_b32 v84, v84, v71
	v_ashrrev_i32_e32 v133, 31, v132
	s_waitcnt lgkmcnt(1)
	v_lshlrev_b64 v[86:87], 12, v[132:133]
	v_lshl_add_u64 v[68:69], s[8:9], 0, v[86:87]
	v_lshl_add_u64 v[86:87], v[190:191], 1, v[68:69]
	s_waitcnt lgkmcnt(0)
	v_add_f32_e32 v68, v71, v84
	ds_bpermute_b32 v69, v85, v68
	v_cvt_pk_bf16_f32 v70, v72, v73
	v_cvt_pk_bf16_f32 v71, v74, v75
	v_cvt_pk_bf16_f32 v72, v82, v83
	v_cvt_pk_bf16_f32 v73, v80, v81
	global_store_dwordx4 v[86:87], v[76:79], off
	global_store_dwordx4 v[86:87], v[70:73], off offset:256
	s_and_saveexec_b64 s[2:3], s[0:1]
	s_cbranch_execz .LBB0_1500
	v_lshl_add_u64 v[70:71], v[194:195], 2, s[6:7]
	s_waitcnt lgkmcnt(0)
	v_add_f32_e32 v68, v68, v69
	global_atomic_add_f32 v[70:71], v68, off offset:192

;     __device__ __forceinline__ void operator()(const f32x4 (&acc)[2][2][4][2], const Unit& u, int wr, int wc, int fr, int fq) const {
;     ...
;         for (int aih = 0; aih < 4; ++aih) { const int ai = aih >> 1, m0 = (aih & 1) * 2;
;             f32x4 rv[4][2][2];
;             if (rb16) {
;                 u32x4 rw[2][2];
; #pragma unroll
;                 for (int m = m0; m < m0 + 2; ++m)
; #pragma unroll
;                     for (int bj = 0; bj < 2; ++bj) rw[m - m0][bj] = *(const u32x4*)((const bf16_t*)r0 + (size_t)(row0 + ai * HALF + m * 16) * D + col0 + bj * HALF);
; #pragma unroll
;                 for (int m = m0; m < m0 + 2; ++m)
; #pragma unroll
;                     for (int bj = 0; bj < 2; ++bj) { const u32x4 x = rw[m - m0][bj];
;                         rv[m][bj][0] = (f32x4){__builtin_bit_cast(float, x.x << 16), __builtin_bit_cast(float, x.x & 0xffff0000u), __builtin_bit_cast(float, x.y << 16), __builtin_bit_cast(float, x.y & 0xffff0000u)};
;                         rv[m][bj][1] = (f32x4){__builtin_bit_cast(float, x.z << 16), __builtin_bit_cast(float, x.z & 0xffff0000u), __builtin_bit_cast(float, x.w << 16), __builtin_bit_cast(float, x.w & 0xffff0000u)}; }
;             } else {
; #pragma unroll
;                 for (int m = m0; m < m0 + 2; ++m) { const float* rp = (const float*)r0 + (size_t)(row0 + ai * HALF + m * 16) * D + col0;
; #pragma unroll
;                     for (int bj = 0; bj < 2; ++bj) { rv[m][bj][0] = *(const f32x4*)(rp + bj * HALF); rv[m][bj][1] = *(const f32x4*)(rp + bj * HALF + 4); } }
;             }
; #pragma unroll
;             for (int m = m0; m < m0 + 2; ++m) { const int row = row0 + ai * HALF + m * 16;
;                 float ss = 0.f;
; #pragma unroll
;                 for (int bj = 0; bj < 2; ++bj) { const f32x4 v0 = acc[ai][bj][m][0] + rv[m][bj][0], v1 = acc[ai][bj][m][1] + rv[m][bj][1];
;                     if (out) { float* op = out + (size_t)row * D + col0 + bj * HALF; *(f32x4*)op = v0; *(f32x4*)(op + 4) = v1; }
;                     if (Hn) { ss += (v0[0] * v0[0] + v0[1] * v0[1]) + (v0[2] * v0[2] + v0[3] * v0[3]) + (v1[0] * v1[0] + v1[1] * v1[1]) + (v1[2] * v1[2] + v1[3] * v1[3]);
;                         u32x4 w; w.x = cvt_pk_bf16(v0[0], v0[1]); w.y = cvt_pk_bf16(v0[2], v0[3]); w.z = cvt_pk_bf16(v1[0], v1[1]); w.w = cvt_pk_bf16(v1[2], v1[3]);
.LBB0_1503:
	s_waitcnt lgkmcnt(0)
	v_lshlrev_b64 v[68:69], 13, v[104:105]
	v_lshl_add_u64 v[68:69], v[198:199], 0, v[68:69]
	global_load_dwordx4 v[96:99], v[68:69], off offset:16
	global_load_dwordx4 v[88:91], v[68:69], off
	global_load_dwordx4 v[92:95], v[68:69], off offset:528
	global_load_dwordx4 v[84:87], v[68:69], off offset:512
	v_lshl_add_u64 v[68:69], v[198:199], 0, v[196:197]
	s_mov_b64 s[2:3], 0x120000
	v_lshl_add_u64 v[72:73], v[68:69], 0, s[2:3]
	v_add_co_u32_e32 v68, vcc, 0x120000, v68
	v_mov_b64_e32 v[100:101], v[102:103]
	s_nop 0
	v_addc_co_u32_e32 v69, vcc, 0, v69, vcc
	global_load_dwordx4 v[68:71], v[68:69], off
	s_nop 0
	global_load_dwordx4 v[76:79], v[72:73], off offset:528
	global_load_dwordx4 v[80:83], v[72:73], off offset:16
	s_nop 0
	global_load_dwordx4 v[72:75], v[72:73], off offset:512
	s_waitcnt vmcnt(0)
.LBB0_1504:
	s_and_b64 vcc, exec, s[44:45]
	s_cbranch_vccnz .Lepi_skip_1510
	v_pk_add_f32 v[62:63], v[62:63], v[90:91]
	v_pk_add_f32 v[60:61], v[60:61], v[88:89]
	v_mul_f32_e32 v89, v63, v63
	v_mul_f32_e32 v88, v61, v61
	v_pk_add_f32 v[64:65], v[64:65], v[96:97]
	v_fmac_f32_e32 v88, v60, v60
	v_fmac_f32_e32 v89, v62, v62
	v_add_f32_e32 v88, v88, v89
	v_mul_f32_e32 v89, v65, v65
	v_pk_add_f32 v[66:67], v[66:67], v[98:99]
	v_fmac_f32_e32 v89, v64, v64
	v_add_f32_e32 v88, v89, v88
	v_mul_f32_e32 v89, v67, v67
	v_pk_add_f32 v[58:59], v[58:59], v[86:87]
	v_pk_add_f32 v[56:57], v[56:57], v[84:85]
	v_fmac_f32_e32 v89, v66, v66
	v_cvt_pk_bf16_f32 v60, v60, v61
	v_cvt_pk_bf16_f32 v61, v62, v63
	v_cvt_pk_bf16_f32 v62, v64, v65
	v_cvt_pk_bf16_f32 v63, v66, v67
	v_pk_add_f32 v[64:65], v[54:55], v[94:95]
	v_pk_add_f32 v[66:67], v[52:53], v[92:93]
	v_mul_f32_e32 v53, v57, v57
	v_mul_f32_e32 v54, v59, v59
	v_fmac_f32_e32 v53, v56, v56
	v_fmac_f32_e32 v54, v58, v58
	v_add_f32_e32 v53, v53, v54
	v_mul_f32_e32 v54, v67, v67
	v_mul_f32_e32 v52, v65, v65
	v_fmac_f32_e32 v54, v66, v66
	v_fmac_f32_e32 v52, v64, v64
	v_add_f32_e32 v53, v54, v53
	v_add_f32_e32 v88, v89, v88
	v_add_f32_e32 v52, v52, v53
	v_and_b32_e32 v54, 64, v218
	v_add_f32_e32 v53, v52, v88
	v_xor_b32_e32 v52, 16, v218
	v_add_u32_e32 v86, 64, v54
	v_cmp_lt_i32_e32 vcc, v52, v86
	s_waitcnt lgkmcnt(0)
	v_lshl_add_u64 v[54:55], s[8:9], 0, v[100:101]
	v_lshl_add_u64 v[84:85], v[190:191], 1, v[54:55]
	v_cndmask_b32_e32 v52, v218, v52, vcc
	v_lshlrev_b32_e32 v52, 2, v52
	ds_bpermute_b32 v87, v52, v53
	v_cvt_pk_bf16_f32 v56, v56, v57
	v_cvt_pk_bf16_f32 v57, v58, v59
	v_cvt_pk_bf16_f32 v58, v66, v67
	v_cvt_pk_bf16_f32 v59, v64, v65
	s_waitcnt lgkmcnt(0)
	v_add_f32_e32 v54, v53, v87
	v_xor_b32_e32 v53, 32, v218
	v_cmp_lt_i32_e32 vcc, v53, v86
	global_store_dwordx4 v[84:85], v[60:63], off
	global_store_dwordx4 v[84:85], v[56:59], off offset:256
	v_cndmask_b32_e32 v53, v218, v53, vcc
	v_lshlrev_b32_e32 v53, 2, v53
	ds_bpermute_b32 v55, v53, v54
	s_and_saveexec_b64 s[2:3], s[0:1]
	s_cbranch_execz .LBB0_1507
	v_lshl_add_u64 v[56:57], v[194:195], 2, s[6:7]
	s_waitcnt lgkmcnt(0)
	v_add_f32_e32 v54, v54, v55
	global_atomic_add_f32 v[56:57], v54, off offset:512
.LBB0_1507:
	s_or_b64 exec, exec, s[2:3]
	v_pk_add_f32 v[46:47], v[46:47], v[70:71]
	v_pk_add_f32 v[44:45], v[44:45], v[68:69]
	s_waitcnt lgkmcnt(0)
	v_mul_f32_e32 v55, v47, v47
	v_mul_f32_e32 v54, v45, v45
	v_pk_add_f32 v[48:49], v[48:49], v[80:81]
	v_fmac_f32_e32 v54, v44, v44
	v_fmac_f32_e32 v55, v46, v46
	v_add_f32_e32 v54, v54, v55
	v_mul_f32_e32 v55, v49, v49
	v_pk_add_f32 v[50:51], v[50:51], v[82:83]
	v_fmac_f32_e32 v55, v48, v48
	v_add_f32_e32 v54, v55, v54
	v_mul_f32_e32 v55, v51, v51
	v_fmac_f32_e32 v55, v50, v50
	v_pk_add_f32 v[42:43], v[42:43], v[74:75]
	v_pk_add_f32 v[40:41], v[40:41], v[72:73]
	v_add_f32_e32 v58, v55, v54
	v_pk_add_f32 v[54:55], v[38:39], v[78:79]
	v_pk_add_f32 v[56:57], v[36:37], v[76:77]
	v_mul_f32_e32 v37, v41, v41
	v_mul_f32_e32 v38, v43, v43
	v_fmac_f32_e32 v37, v40, v40
	v_fmac_f32_e32 v38, v42, v42
	v_add_f32_e32 v37, v37, v38
	v_mul_f32_e32 v38, v57, v57
	v_mul_f32_e32 v36, v55, v55
	v_fmac_f32_e32 v38, v56, v56
	v_fmac_f32_e32 v36, v54, v54
	v_add_f32_e32 v37, v38, v37
	v_add_f32_e32 v36, v36, v37
	v_add_f32_e32 v39, v36, v58
	v_cvt_pk_bf16_f32 v44, v44, v45
	v_cvt_pk_bf16_f32 v45, v46, v47
	v_cvt_pk_bf16_f32 v46, v48, v49
	v_lshl_add_u64 v[48:49], s[8:9], 0, v[192:193]
	ds_bpermute_b32 v52, v52, v39
	v_lshl_add_u64 v[48:49], v[190:191], 1, v[48:49]
	s_mov_b64 s[2:3], 0x90000
	v_cvt_pk_bf16_f32 v47, v50, v51
	v_lshl_add_u64 v[50:51], v[48:49], 0, s[2:3]
	s_mov_b32 s2, 0x90000
	v_add_co_u32_e32 v36, vcc, s2, v48
	v_cvt_pk_bf16_f32 v38, v40, v41
	s_nop 0
	v_addc_co_u32_e32 v37, vcc, 0, v49, vcc
	global_store_dwordx4 v[36:37], v[44:47], off
	s_waitcnt lgkmcnt(0)
	v_add_f32_e32 v36, v39, v52
	ds_bpermute_b32 v37, v53, v36
	v_cvt_pk_bf16_f32 v39, v42, v43
	v_cvt_pk_bf16_f32 v40, v56, v57
	v_cvt_pk_bf16_f32 v41, v54, v55
	global_store_dwordx4 v[50:51], v[38:41], off offset:256
	s_and_saveexec_b64 s[2:3], s[0:1]
	s_cbranch_execz .LBB0_1509
	v_lshl_add_u64 v[38:39], v[194:195], 2, s[6:7]
	s_waitcnt lgkmcnt(0)
	v_add_f32_e32 v36, v36, v37
	global_atomic_add_f32 v[38:39], v36, off offset:576

;     __device__ __forceinline__ void operator()(const f32x4 (&acc)[2][2][4][2], const Unit& u, int wr, int wc, int fr, int fq) const {
;     ...
;         for (int aih = 0; aih < 4; ++aih) { const int ai = aih >> 1, m0 = (aih & 1) * 2;
;             f32x4 rv[4][2][2];
;             if (rb16) {
;                 u32x4 rw[2][2];
; #pragma unroll
;                 for (int m = m0; m < m0 + 2; ++m)
; #pragma unroll
;                     for (int bj = 0; bj < 2; ++bj) rw[m - m0][bj] = *(const u32x4*)((const bf16_t*)r0 + (size_t)(row0 + ai * HALF + m * 16) * D + col0 + bj * HALF);
; #pragma unroll
;                 for (int m = m0; m < m0 + 2; ++m)
; #pragma unroll
;                     for (int bj = 0; bj < 2; ++bj) { const u32x4 x = rw[m - m0][bj];
;                         rv[m][bj][0] = (f32x4){__builtin_bit_cast(float, x.x << 16), __builtin_bit_cast(float, x.x & 0xffff0000u), __builtin_bit_cast(float, x.y << 16), __builtin_bit_cast(float, x.y & 0xffff0000u)};
;                         rv[m][bj][1] = (f32x4){__builtin_bit_cast(float, x.z << 16), __builtin_bit_cast(float, x.z & 0xffff0000u), __builtin_bit_cast(float, x.w << 16), __builtin_bit_cast(float, x.w & 0xffff0000u)}; }
;             } else {
; #pragma unroll
;                 for (int m = m0; m < m0 + 2; ++m) { const float* rp = (const float*)r0 + (size_t)(row0 + ai * HALF + m * 16) * D + col0;
; #pragma unroll
;                     for (int bj = 0; bj < 2; ++bj) { rv[m][bj][0] = *(const f32x4*)(rp + bj * HALF); rv[m][bj][1] = *(const f32x4*)(rp + bj * HALF + 4); } }
;             }
; #pragma unroll
;             for (int m = m0; m < m0 + 2; ++m) { const int row = row0 + ai * HALF + m * 16;
;                 float ss = 0.f;
; #pragma unroll
;                 for (int bj = 0; bj < 2; ++bj) { const f32x4 v0 = acc[ai][bj][m][0] + rv[m][bj][0], v1 = acc[ai][bj][m][1] + rv[m][bj][1];
;                     if (out) { float* op = out + (size_t)row * D + col0 + bj * HALF; *(f32x4*)op = v0; *(f32x4*)(op + 4) = v1; }
;                     if (Hn) { ss += (v0[0] * v0[0] + v0[1] * v0[1]) + (v0[2] * v0[2] + v0[3] * v0[3]) + (v1[0] * v1[0] + v1[1] * v1[1]) + (v1[2] * v1[2] + v1[3] * v1[3]);
;                         u32x4 w; w.x = cvt_pk_bf16(v0[0], v0[1]); w.y = cvt_pk_bf16(v0[2], v0[3]); w.z = cvt_pk_bf16(v1[0], v1[1]); w.w = cvt_pk_bf16(v1[2], v1[3]);
.LBB0_1512:
	v_lshlrev_b64 v[36:37], 13, v[72:73]
	v_lshl_add_u64 v[36:37], v[198:199], 0, v[36:37]
	global_load_dwordx4 v[64:67], v[36:37], off offset:16
	global_load_dwordx4 v[56:59], v[36:37], off
	global_load_dwordx4 v[60:63], v[36:37], off offset:528
	global_load_dwordx4 v[52:55], v[36:37], off offset:512
	v_lshl_add_u64 v[36:37], v[198:199], 0, v[196:197]
	s_mov_b64 s[2:3], 0x160000
	v_lshl_add_u64 v[40:41], v[36:37], 0, s[2:3]
	v_add_co_u32_e32 v36, vcc, 0x160000, v36
	v_mov_b64_e32 v[70:71], v[68:69]
	s_nop 0
	v_addc_co_u32_e32 v37, vcc, 0, v37, vcc
	global_load_dwordx4 v[36:39], v[36:37], off
	s_nop 0
	global_load_dwordx4 v[44:47], v[40:41], off offset:528
	global_load_dwordx4 v[48:51], v[40:41], off offset:16
	s_nop 0
	global_load_dwordx4 v[40:43], v[40:41], off offset:512
	s_waitcnt vmcnt(0)
.LBB0_1513:
	s_and_b64 vcc, exec, s[44:45]
	s_cbranch_vccnz .LBB0_1519
	v_pk_add_f32 v[28:29], v[28:29], v[58:59]
	v_pk_add_f32 v[26:27], v[26:27], v[56:57]
	v_mul_f32_e32 v57, v29, v29
	v_mul_f32_e32 v56, v27, v27
	v_pk_add_f32 v[30:31], v[30:31], v[64:65]
	v_fmac_f32_e32 v56, v26, v26
	v_fmac_f32_e32 v57, v28, v28
	v_add_f32_e32 v56, v56, v57
	v_mul_f32_e32 v57, v31, v31
	v_pk_add_f32 v[32:33], v[32:33], v[66:67]
	v_fmac_f32_e32 v57, v30, v30
	v_add_f32_e32 v56, v57, v56
	v_mul_f32_e32 v57, v33, v33
	v_fmac_f32_e32 v57, v32, v32
	v_cvt_pk_bf16_f32 v26, v26, v27
	v_cvt_pk_bf16_f32 v27, v28, v29
	v_cvt_pk_bf16_f32 v29, v32, v33
	v_pk_add_f32 v[32:33], v[24:25], v[54:55]
	v_pk_add_f32 v[22:23], v[22:23], v[52:53]
	v_pk_add_f32 v[52:53], v[20:21], v[62:63]
	v_mul_f32_e32 v21, v23, v23
	v_mul_f32_e32 v24, v33, v33
	v_pk_add_f32 v[18:19], v[18:19], v[60:61]
	v_fmac_f32_e32 v21, v22, v22
	v_fmac_f32_e32 v24, v32, v32
	v_add_f32_e32 v21, v21, v24
	v_mul_f32_e32 v24, v19, v19
	v_mul_f32_e32 v20, v53, v53
	v_fmac_f32_e32 v24, v18, v18
	v_fmac_f32_e32 v20, v52, v52
	v_add_f32_e32 v21, v24, v21
	v_add_f32_e32 v56, v57, v56
	v_add_f32_e32 v20, v20, v21
	v_and_b32_e32 v24, 64, v218
	v_add_f32_e32 v21, v20, v56
	v_xor_b32_e32 v20, 16, v218
	v_add_u32_e32 v54, 64, v24
	v_cmp_lt_i32_e32 vcc, v20, v54
	v_cvt_pk_bf16_f32 v24, v22, v23
	v_cvt_pk_bf16_f32 v28, v30, v31
	v_cndmask_b32_e32 v20, v218, v20, vcc
	v_lshlrev_b32_e32 v20, 2, v20
	ds_bpermute_b32 v55, v20, v21
	v_lshl_add_u64 v[30:31], s[8:9], 0, v[70:71]
	v_lshl_add_u64 v[30:31], v[190:191], 1, v[30:31]
	global_store_dwordx4 v[30:31], v[26:29], off
	v_cvt_pk_bf16_f32 v25, v32, v33
	s_waitcnt lgkmcnt(0)
	v_add_f32_e32 v22, v21, v55
	v_xor_b32_e32 v21, 32, v218
	v_cmp_lt_i32_e32 vcc, v21, v54
	v_cvt_pk_bf16_f32 v26, v18, v19
	v_cvt_pk_bf16_f32 v27, v52, v53
	v_cndmask_b32_e32 v21, v218, v21, vcc
	v_lshlrev_b32_e32 v21, 2, v21
	ds_bpermute_b32 v23, v21, v22
	v_lshl_add_u64 v[18:19], v[194:195], 2, s[6:7]
	global_store_dwordx4 v[30:31], v[24:27], off offset:256
	s_and_saveexec_b64 s[2:3], s[0:1]
	s_cbranch_execz .LBB0_1516
	s_waitcnt lgkmcnt(0)
	v_add_f32_e32 v22, v22, v23
	global_atomic_add_f32 v[18:19], v22, off offset:640
.LBB0_1516:
	s_or_b64 exec, exec, s[2:3]
	v_pk_add_f32 v[12:13], v[12:13], v[38:39]
	v_pk_add_f32 v[10:11], v[10:11], v[36:37]
	s_waitcnt lgkmcnt(0)
	v_mul_f32_e32 v23, v13, v13
	v_mul_f32_e32 v22, v11, v11
	v_pk_add_f32 v[14:15], v[14:15], v[48:49]
	v_fmac_f32_e32 v22, v10, v10
	v_fmac_f32_e32 v23, v12, v12
	v_add_f32_e32 v22, v22, v23
	v_mul_f32_e32 v23, v15, v15
	v_pk_add_f32 v[16:17], v[16:17], v[50:51]
	v_fmac_f32_e32 v23, v14, v14
	v_add_f32_e32 v22, v23, v22
	v_mul_f32_e32 v23, v17, v17
	v_fmac_f32_e32 v23, v16, v16
	v_pk_add_f32 v[8:9], v[8:9], v[42:43]
	v_pk_add_f32 v[6:7], v[6:7], v[40:41]
	v_add_f32_e32 v26, v23, v22
	v_pk_add_f32 v[22:23], v[4:5], v[46:47]
	v_pk_add_f32 v[24:25], v[2:3], v[44:45]
	v_mul_f32_e32 v3, v7, v7
	v_mul_f32_e32 v4, v9, v9
	v_fmac_f32_e32 v3, v6, v6
	v_fmac_f32_e32 v4, v8, v8
	v_add_f32_e32 v3, v3, v4
	v_mul_f32_e32 v4, v25, v25
	v_mul_f32_e32 v2, v23, v23
	v_fmac_f32_e32 v4, v24, v24
	v_fmac_f32_e32 v2, v22, v22
	v_add_f32_e32 v3, v4, v3
	v_add_f32_e32 v2, v2, v3
	v_add_f32_e32 v5, v2, v26
	v_cvt_pk_bf16_f32 v10, v10, v11
	v_cvt_pk_bf16_f32 v11, v12, v13
	v_cvt_pk_bf16_f32 v12, v14, v15
	v_lshl_add_u64 v[14:15], s[8:9], 0, v[192:193]
	ds_bpermute_b32 v20, v20, v5
	v_lshl_add_u64 v[14:15], v[190:191], 1, v[14:15]
	s_mov_b64 s[2:3], 0xb0000
	v_cvt_pk_bf16_f32 v13, v16, v17
	v_lshl_add_u64 v[16:17], v[14:15], 0, s[2:3]
	s_mov_b32 s2, 0xb0000
	v_add_co_u32_e32 v2, vcc, s2, v14
	v_cvt_pk_bf16_f32 v4, v6, v7
	s_nop 0
	v_addc_co_u32_e32 v3, vcc, 0, v15, vcc
	global_store_dwordx4 v[2:3], v[10:13], off
	s_waitcnt lgkmcnt(0)
	v_add_f32_e32 v2, v5, v20
	ds_bpermute_b32 v3, v21, v2
	v_cvt_pk_bf16_f32 v5, v8, v9
	v_cvt_pk_bf16_f32 v6, v24, v25
	v_cvt_pk_bf16_f32 v7, v22, v23
	global_store_dwordx4 v[16:17], v[4:7], off offset:256
	s_and_saveexec_b64 s[2:3], s[0:1]
	s_cbranch_execz .LBB0_1518
	s_waitcnt lgkmcnt(0)
	v_add_f32_e32 v2, v2, v3
	global_atomic_add_f32 v[18:19], v2, off offset:704
